# attention phase: static s_setprio 1 for waves 4-7 (stagger SIMD partners), reset at conv start
# baseline (speedup 1.0000x reference)
.LBB0_457:
	s_cmp_ge_u32 s93, 4
	s_cbranch_scc0 .Lattn_prio_skip
	s_setprio 1

.LBB0_498:
	s_setprio 0
	v_mbcnt_lo_u32_b32 v0, -1, 0
	v_mbcnt_hi_u32_b32 v0, -1, v0
	s_mov_b64 s[14:15], s[96:97]
	v_add_u32_e32 v6, s73, v0
	s_load_dwordx4 s[16:19], s[14:15], 0xd8
	s_load_dwordx2 s[40:41], s[14:15], 0x20
	s_load_dwordx8 s[4:11], s[14:15], 0x78
	s_movk_i32 s13, 0x1680
	v_cmp_gt_i32_e32 vcc, s13, v6
	s_and_saveexec_b64 s[22:23], vcc
	s_cbranch_execz .LBB0_503
	v_lshl_add_u32 v7, v6, 4, 0
	s_mov_b64 s[42:43], 0
	s_movk_i32 s13, 0xf80
	v_mov_b32_e32 v5, 0
	s_movk_i32 s14, 0x147f
	v_mov_b32_e32 v4, v6
	s_branch .LBB0_501
